# prep phase prologue: the 64 serialised (load,load,wait,cvt) weight-fragment groups issued as 4 batches of 16 pairs with one wait each
# speedup vs baseline: 1.0052x; 1.0052x over previous
.LBB0_168:
	s_and_b64 vcc, exec, s[0:1]
	s_cbranch_vccz .LBB0_234
	v_readlane_b32 s0, v255, 18
	s_cmp_gt_i32 s0, 0
	s_mov_b64 s[0:1], -1
	s_cbranch_scc0 .LBB0_252
	v_readlane_b32 s0, v255, 18
	s_cmp_gt_i32 s0, 1
	s_mov_b64 s[0:1], -1
	s_cbranch_scc0 .LBB0_236
	s_cmpk_gt_i32 s88, 0x1ff
	s_cbranch_scc1 .LBB0_235
	v_readlane_b32 s0, v255, 16
	s_mov_b32 s20, s0
	s_ashr_i32 s21, s0, 31
	v_readlane_b32 s60, v253, 23
	s_lshl_b64 s[2:3], s[20:21], 16
	v_readlane_b32 s66, v253, 29
	v_readlane_b32 s1, v255, 17
	v_readlane_b32 s67, v253, 30
	s_add_u32 s0, s66, s2
	v_readlane_b32 s70, v253, 33
	s_addc_u32 s1, s67, s3
	v_readlane_b32 s71, v253, 34
	s_add_u32 s38, s70, s2
	s_mul_i32 s2, s20, 0x380
	s_addc_u32 s39, s71, s3
	s_ashr_i32 s3, s2, 31
	v_readlane_b32 s62, v253, 25
	s_lshl_b64 s[2:3], s[2:3], 2
	v_readlane_b32 s63, v253, 26
	s_add_u32 s2, s62, s2
	s_addc_u32 s3, s63, s3
	v_ashrrev_i32_e32 v161, 31, v160
	v_lshl_add_u64 v[0:1], v[160:161], 2, s[2:3]
	v_and_b32_e32 v68, 0x7f, v160
	global_load_dword v69, v[0:1], off
	global_load_dword v71, v[0:1], off offset:1024
	global_load_dword v126, v[0:1], off offset:2048
	v_lshlrev_b32_e32 v0, 2, v68
	global_load_dword v127, v0, s[2:3] offset:3072
	v_lshl_add_u32 v0, s20, 8, v160
	v_ashrrev_i32_e32 v1, 31, v0
	v_readlane_b32 s64, v253, 27
	v_readlane_b32 s65, v253, 28
	s_waitcnt vmcnt(6)
	v_lshlrev_b64 v[4:5], 2, v[0:1]
	v_readlane_b32 s68, v253, 31
	v_readlane_b32 s69, v253, 32
	v_lshl_add_u64 v[6:7], s[64:65], 0, v[4:5]
	v_readlane_b32 s72, v253, 35
	v_readlane_b32 s73, v253, 36
	global_load_dword v128, v[6:7], off
	v_lshl_add_u64 v[6:7], s[68:69], 0, v[4:5]
	v_readlane_b32 s4, v254, 62
	v_lshl_add_u32 v0, s20, 9, v0
	v_bfe_u32 v136, v160, 4, 2
	v_readlane_b32 s61, v253, 24
	v_readlane_b32 s74, v253, 37
	v_readlane_b32 s75, v253, 38
	global_load_dword v129, v[6:7], off
	v_lshl_add_u64 v[6:7], s[72:73], 0, v[4:5]
	v_readlane_b32 s5, v254, 63
	v_ashrrev_i32_e32 v1, 31, v0
	v_lshlrev_b32_e32 v2, 11, v136
	global_load_dword v130, v[6:7], off
	v_lshl_add_u64 v[6:7], s[74:75], 0, v[4:5]
	v_lshl_add_u64 v[4:5], s[4:5], 0, v[4:5]
	v_lshl_add_u64 v[0:1], v[0:1], 2, s[60:61]
	v_or_b32_e32 v55, 0x2000, v2
	v_or_b32_e32 v76, 48, v160
	global_load_dword v131, v[6:7], off
	global_load_dword v132, v[4:5], off
	global_load_dword v133, v[0:1], off
	global_load_dword v134, v[0:1], off offset:1024
	global_load_dword v135, v[0:1], off offset:2048
	v_add_u32_e32 v0, v55, v76
	v_ashrrev_i32_e32 v1, 31, v0
	v_lshlrev_b64 v[0:1], 2, v[0:1]
	v_lshl_add_u64 v[4:5], s[38:39], 0, v[0:1]
	v_add_u32_e32 v24, 0x100, v76
	global_load_dword v202, v[4:5], off
	v_add_u32_e32 v4, v55, v24
	v_ashrrev_i32_e32 v5, 31, v4
	v_lshlrev_b64 v[8:9], 2, v[4:5]
	v_lshl_add_u64 v[4:5], s[38:39], 0, v[8:9]
	global_load_dword v203, v[4:5], off
	v_add_u32_e32 v25, 0x200, v76
	v_add_u32_e32 v26, 0x300, v76
	v_add_u32_e32 v27, 0x400, v76
	v_add_u32_e32 v28, 0x500, v76
	v_add_u32_e32 v29, 0x600, v76
	v_add_u32_e32 v30, 0x700, v76
	v_lshl_add_u64 v[0:1], s[0:1], 0, v[0:1]
	v_and_b32_e32 v70, 63, v160
	v_cmp_eq_u32_e64 s[40:41], 0, v70
	v_bfe_u32 v70, v160, 5, 2
	s_mov_b32 s2, s20
	v_readlane_b32 s60, v254, 44
	v_readlane_b32 s65, v254, 49
	v_readlane_b32 s69, v254, 53
	v_readlane_b32 s64, v254, 48
	v_readlane_b32 s68, v254, 52
	v_bfe_u32 v139, v160, 3, 2
	v_readlane_b32 s67, v254, 51
	v_readlane_b32 s71, v254, 55
	v_readlane_b32 s66, v254, 50
	v_readlane_b32 s70, v254, 54
	v_and_b32_e32 v88, 15, v160
	v_readlane_b32 s6, v255, 0
	v_readlane_b32 s7, v255, 1
	v_readlane_b32 s8, v255, 2
	v_readlane_b32 s9, v255, 3
	v_readlane_b32 s10, v255, 4
	v_readlane_b32 s11, v255, 5
	v_readlane_b32 s12, v255, 6
	v_readlane_b32 s13, v255, 7
	v_readlane_b32 s14, v255, 8
	v_readlane_b32 s15, v255, 9
	v_readlane_b32 s16, v255, 10
	v_readlane_b32 s17, v255, 11
	v_readlane_b32 s18, v255, 12
	v_readlane_b32 s19, v255, 13
	v_writelane_b32 v255, s2, 16
	v_lshlrev_b32_e32 v94, 1, v68
	v_mul_u32_u24_e32 v95, 0x110, v88
	v_and_b32_e32 v96, 48, v160
	v_ashrrev_i32_e32 v144, 5, v160
	v_lshlrev_b32_e32 v151, 1, v160
	v_readlane_b32 s72, v254, 56
	v_readlane_b32 s73, v254, 57
	v_readlane_b32 s74, v254, 58
	v_readlane_b32 s75, v254, 59
	s_lshl_b32 s21, s88, 6
	v_writelane_b32 v255, s3, 17
	v_ashrrev_i32_e32 v138, 1, v160
	v_and_b32_e32 v142, 3, v160
	v_add_u32_e32 v152, v151, v151
	v_add_u32_e32 v154, s21, v144
	v_lshlrev_b32_e32 v88, 4, v88
	v_mov_b32_e32 v89, v3
	v_add_u32_e32 v155, v95, v96
	s_mov_b32 s59, s88
	v_readlane_b32 s61, v254, 45
	v_readlane_b32 s62, v254, 46
	v_readlane_b32 s63, v254, 47
	v_add_u32_e32 v6, v55, v25
	v_ashrrev_i32_e32 v7, 31, v6
	v_lshlrev_b64 v[10:11], 2, v[6:7]
	v_lshl_add_u64 v[6:7], s[38:39], 0, v[10:11]
	global_load_dword v204, v[6:7], off
	v_add_u32_e32 v6, v55, v26
	v_ashrrev_i32_e32 v7, 31, v6
	v_lshlrev_b64 v[12:13], 2, v[6:7]
	v_lshl_add_u64 v[6:7], s[38:39], 0, v[12:13]
	global_load_dword v205, v[6:7], off
	v_add_u32_e32 v6, v55, v27
	v_ashrrev_i32_e32 v7, 31, v6
	v_lshlrev_b64 v[14:15], 2, v[6:7]
	v_lshl_add_u64 v[6:7], s[38:39], 0, v[14:15]
	global_load_dword v206, v[6:7], off
	v_add_u32_e32 v6, v55, v28
	v_ashrrev_i32_e32 v7, 31, v6
	v_lshlrev_b64 v[16:17], 2, v[6:7]
	v_lshl_add_u64 v[6:7], s[38:39], 0, v[16:17]
	global_load_dword v207, v[6:7], off
	v_add_u32_e32 v18, v55, v29
	v_ashrrev_i32_e32 v19, 31, v18
	v_lshlrev_b64 v[18:19], 2, v[18:19]
	v_lshl_add_u64 v[20:21], s[38:39], 0, v[18:19]
	global_load_dword v208, v[20:21], off
	v_add_u32_e32 v20, v55, v30
	v_ashrrev_i32_e32 v21, 31, v20
	v_lshlrev_b64 v[20:21], 2, v[20:21]
	v_lshl_add_u64 v[22:23], s[38:39], 0, v[20:21]
	global_load_dword v209, v[22:23], off
	global_load_dword v210, v[0:1], off
	v_lshl_add_u64 v[0:1], s[0:1], 0, v[8:9]
	global_load_dword v211, v[0:1], off
	v_lshl_add_u64 v[0:1], s[0:1], 0, v[10:11]
	global_load_dword v212, v[0:1], off
	v_lshl_add_u64 v[0:1], s[0:1], 0, v[12:13]
	global_load_dword v213, v[0:1], off
	v_lshl_add_u64 v[0:1], s[0:1], 0, v[14:15]
	global_load_dword v214, v[0:1], off
	v_lshl_add_u64 v[0:1], s[0:1], 0, v[16:17]
	global_load_dword v215, v[0:1], off
	v_lshl_add_u64 v[0:1], s[0:1], 0, v[18:19]
	global_load_dword v216, v[0:1], off
	v_lshl_add_u64 v[0:1], s[0:1], 0, v[20:21]
	global_load_dword v217, v[0:1], off
	v_add_u32_e32 v0, v2, v76
	v_ashrrev_i32_e32 v1, 31, v0
	v_lshlrev_b64 v[0:1], 2, v[0:1]
	v_lshl_add_u64 v[12:13], s[38:39], 0, v[0:1]
	global_load_dword v218, v[12:13], off
	v_add_u32_e32 v12, v2, v24
	v_ashrrev_i32_e32 v13, 31, v12
	v_lshlrev_b64 v[16:17], 2, v[12:13]
	v_lshl_add_u64 v[12:13], s[38:39], 0, v[16:17]
	global_load_dword v219, v[12:13], off
	v_lshl_add_u64 v[0:1], s[0:1], 0, v[0:1]
	v_add_u32_e32 v14, v2, v25
	v_ashrrev_i32_e32 v15, 31, v14
	v_lshlrev_b64 v[18:19], 2, v[14:15]
	v_lshl_add_u64 v[14:15], s[38:39], 0, v[18:19]
	global_load_dword v220, v[14:15], off
	v_add_u32_e32 v14, v2, v26
	v_ashrrev_i32_e32 v15, 31, v14
	v_lshlrev_b64 v[20:21], 2, v[14:15]
	v_lshl_add_u64 v[14:15], s[38:39], 0, v[20:21]
	global_load_dword v221, v[14:15], off
	v_add_u32_e32 v14, v2, v27
	v_ashrrev_i32_e32 v15, 31, v14
	v_lshlrev_b64 v[22:23], 2, v[14:15]
	v_lshl_add_u64 v[14:15], s[38:39], 0, v[22:23]
	global_load_dword v222, v[14:15], off
	v_add_u32_e32 v14, v2, v28
	v_ashrrev_i32_e32 v15, 31, v14
	v_lshlrev_b64 v[24:25], 2, v[14:15]
	v_lshl_add_u64 v[14:15], s[38:39], 0, v[24:25]
	global_load_dword v223, v[14:15], off
	v_add_u32_e32 v26, v2, v29
	v_ashrrev_i32_e32 v27, 31, v26
	v_lshlrev_b64 v[26:27], 2, v[26:27]
	v_lshl_add_u64 v[28:29], s[38:39], 0, v[26:27]
	global_load_dword v224, v[28:29], off
	v_add_u32_e32 v28, v2, v30
	v_ashrrev_i32_e32 v29, 31, v28
	v_lshlrev_b64 v[28:29], 2, v[28:29]
	v_lshl_add_u64 v[30:31], s[38:39], 0, v[28:29]
	global_load_dword v225, v[30:31], off
	global_load_dword v226, v[0:1], off
	v_lshl_add_u64 v[0:1], s[0:1], 0, v[16:17]
	global_load_dword v227, v[0:1], off
	v_lshl_add_u64 v[0:1], s[0:1], 0, v[18:19]
	global_load_dword v228, v[0:1], off
	v_lshl_add_u64 v[0:1], s[0:1], 0, v[20:21]
	global_load_dword v229, v[0:1], off
	v_lshl_add_u64 v[0:1], s[0:1], 0, v[22:23]
	global_load_dword v230, v[0:1], off
	v_lshl_add_u64 v[0:1], s[0:1], 0, v[24:25]
	global_load_dword v231, v[0:1], off
	v_lshl_add_u64 v[0:1], s[0:1], 0, v[26:27]
	global_load_dword v232, v[0:1], off
	v_lshl_add_u64 v[0:1], s[0:1], 0, v[28:29]
	global_load_dword v233, v[0:1], off
	s_waitcnt vmcnt(0)
	v_cvt_pk_bf16_f32 v4, v202, v203
	v_cvt_pk_bf16_f32 v5, v204, v205
	v_cvt_pk_bf16_f32 v6, v206, v207
	v_cvt_pk_bf16_f32 v7, v208, v209
	v_cvt_pk_bf16_f32 v8, v210, v211
	v_cvt_pk_bf16_f32 v9, v212, v213
	v_cvt_pk_bf16_f32 v10, v214, v215
	v_cvt_pk_bf16_f32 v11, v216, v217
	v_cvt_pk_bf16_f32 v12, v218, v219
	v_cvt_pk_bf16_f32 v13, v220, v221
	v_cvt_pk_bf16_f32 v14, v222, v223
	v_cvt_pk_bf16_f32 v15, v224, v225
	v_cvt_pk_bf16_f32 v16, v226, v227
	v_cvt_pk_bf16_f32 v17, v228, v229
	v_cvt_pk_bf16_f32 v18, v230, v231
	v_cvt_pk_bf16_f32 v19, v232, v233
	v_and_b32_e32 v0, 0xffffffcf, v160
	v_or_b32_e32 v77, 32, v0
	v_add_u32_e32 v20, v55, v77
	v_ashrrev_i32_e32 v21, 31, v20
	v_lshlrev_b64 v[24:25], 2, v[20:21]
	v_lshl_add_u64 v[20:21], s[38:39], 0, v[24:25]
	v_add_u32_e32 v42, 0x120, v0
	global_load_dword v202, v[20:21], off
	v_add_u32_e32 v20, v55, v42
	v_ashrrev_i32_e32 v21, 31, v20
	v_lshlrev_b64 v[26:27], 2, v[20:21]
	v_lshl_add_u64 v[20:21], s[38:39], 0, v[26:27]
	global_load_dword v203, v[20:21], off
	v_add_u32_e32 v43, 0x220, v0
	v_add_u32_e32 v22, v55, v43
	v_ashrrev_i32_e32 v23, 31, v22
	v_lshlrev_b64 v[28:29], 2, v[22:23]
	v_lshl_add_u64 v[22:23], s[38:39], 0, v[28:29]
	v_add_u32_e32 v46, 0x320, v0
	v_add_u32_e32 v47, 0x420, v0
	v_add_u32_e32 v48, 0x520, v0
	v_add_u32_e32 v49, 0x620, v0
	v_add_u32_e32 v36, v55, v49
	v_ashrrev_i32_e32 v37, 31, v36
	v_lshlrev_b64 v[36:37], 2, v[36:37]
	v_lshl_add_u64 v[38:39], s[38:39], 0, v[36:37]
	v_add_u32_e32 v50, 0x720, v0
	v_lshl_add_u64 v[24:25], s[0:1], 0, v[24:25]
	v_add_u32_e32 v54, 0x110, v0
	v_add_u32_e32 v64, 0x210, v0
	v_add_u32_e32 v65, 0x310, v0
	v_add_u32_e32 v66, 0x410, v0
	v_add_u32_e32 v67, 0x510, v0
	v_add_u32_e32 v72, 0x610, v0
	v_add_u32_e32 v73, 0x710, v0
	v_add_u32_e32 v80, 0x100, v0
	v_add_u32_e32 v81, 0x200, v0
	v_add_u32_e32 v82, 0x300, v0
	v_add_u32_e32 v83, 0x400, v0
	v_add_u32_e32 v84, 0x500, v0
	v_add_u32_e32 v85, 0x600, v0
	v_add_u32_e32 v87, 0x700, v0
	global_load_dword v204, v[22:23], off
	v_add_u32_e32 v22, v55, v46
	v_ashrrev_i32_e32 v23, 31, v22
	v_lshlrev_b64 v[30:31], 2, v[22:23]
	v_lshl_add_u64 v[22:23], s[38:39], 0, v[30:31]
	global_load_dword v205, v[22:23], off
	v_add_u32_e32 v22, v55, v47
	v_ashrrev_i32_e32 v23, 31, v22
	v_lshlrev_b64 v[32:33], 2, v[22:23]
	v_lshl_add_u64 v[22:23], s[38:39], 0, v[32:33]
	global_load_dword v206, v[22:23], off
	v_add_u32_e32 v22, v55, v48
	v_ashrrev_i32_e32 v23, 31, v22
	v_lshlrev_b64 v[34:35], 2, v[22:23]
	v_lshl_add_u64 v[22:23], s[38:39], 0, v[34:35]
	global_load_dword v207, v[22:23], off
	global_load_dword v208, v[38:39], off
	v_add_u32_e32 v38, v55, v50
	v_ashrrev_i32_e32 v39, 31, v38
	v_lshlrev_b64 v[38:39], 2, v[38:39]
	v_lshl_add_u64 v[40:41], s[38:39], 0, v[38:39]
	global_load_dword v209, v[40:41], off
	global_load_dword v210, v[24:25], off
	v_lshl_add_u64 v[24:25], s[0:1], 0, v[26:27]
	global_load_dword v211, v[24:25], off
	v_lshl_add_u64 v[26:27], s[0:1], 0, v[28:29]
	v_lshl_add_u64 v[28:29], s[0:1], 0, v[36:37]
	global_load_dword v212, v[26:27], off
	v_lshl_add_u64 v[26:27], s[0:1], 0, v[30:31]
	global_load_dword v213, v[26:27], off
	v_lshl_add_u64 v[26:27], s[0:1], 0, v[32:33]
	v_add_u32_e32 v30, v2, v43
	v_ashrrev_i32_e32 v31, 31, v30
	v_lshlrev_b64 v[36:37], 2, v[30:31]
	v_lshl_add_u64 v[30:31], s[38:39], 0, v[36:37]
	global_load_dword v214, v[26:27], off
	v_lshl_add_u64 v[26:27], s[0:1], 0, v[34:35]
	global_load_dword v215, v[26:27], off
	global_load_dword v216, v[28:29], off
	v_lshl_add_u64 v[28:29], s[0:1], 0, v[38:39]
	global_load_dword v217, v[28:29], off
	v_ashrrev_i32_e32 v1, 31, v0
	v_lshl_add_u64 v[28:29], v[2:3], 0, v[0:1]
	v_lshlrev_b64 v[32:33], 2, v[28:29]
	v_add_u32_e32 v28, v2, v42
	v_ashrrev_i32_e32 v29, 31, v28
	v_lshlrev_b64 v[34:35], 2, v[28:29]
	v_lshl_add_u64 v[44:45], s[38:39], 0, v[32:33]
	v_lshl_add_u64 v[28:29], s[38:39], 0, v[34:35]
	global_load_dword v218, v[44:45], off offset:128
	s_nop 0
	global_load_dword v219, v[28:29], off
	global_load_dword v220, v[30:31], off
	v_add_u32_e32 v30, v2, v46
	v_ashrrev_i32_e32 v31, 31, v30
	v_lshlrev_b64 v[38:39], 2, v[30:31]
	v_lshl_add_u64 v[30:31], s[38:39], 0, v[38:39]
	global_load_dword v221, v[30:31], off
	v_add_u32_e32 v30, v2, v47
	v_ashrrev_i32_e32 v31, 31, v30
	v_lshlrev_b64 v[40:41], 2, v[30:31]
	v_lshl_add_u64 v[30:31], s[38:39], 0, v[40:41]
	v_add_u32_e32 v46, v2, v49
	v_ashrrev_i32_e32 v47, 31, v46
	v_lshlrev_b64 v[46:47], 2, v[46:47]
	global_load_dword v222, v[30:31], off
	v_add_u32_e32 v30, v2, v48
	v_ashrrev_i32_e32 v31, 31, v30
	v_lshlrev_b64 v[42:43], 2, v[30:31]
	v_lshl_add_u64 v[30:31], s[38:39], 0, v[42:43]
	global_load_dword v223, v[30:31], off
	v_lshl_add_u64 v[48:49], s[38:39], 0, v[46:47]
	global_load_dword v224, v[48:49], off
	v_add_u32_e32 v48, v2, v50
	v_ashrrev_i32_e32 v49, 31, v48
	v_lshlrev_b64 v[50:51], 2, v[48:49]
	v_lshl_add_u64 v[48:49], s[38:39], 0, v[50:51]
	global_load_dword v225, v[48:49], off
	v_lshl_add_u64 v[48:49], s[0:1], 0, v[32:33]
	v_lshl_add_u64 v[32:33], s[0:1], 0, v[34:35]
	global_load_dword v226, v[32:33], off
	v_lshl_add_u64 v[34:35], s[0:1], 0, v[36:37]
	v_lshl_add_u64 v[36:37], s[0:1], 0, v[46:47]
	global_load_dword v227, v[48:49], off offset:128
	global_load_dword v228, v[34:35], off
	v_lshl_add_u64 v[34:35], s[0:1], 0, v[38:39]
	global_load_dword v229, v[34:35], off
	v_lshl_add_u64 v[34:35], s[0:1], 0, v[40:41]
	global_load_dword v230, v[34:35], off
	v_lshl_add_u64 v[34:35], s[0:1], 0, v[42:43]
	global_load_dword v231, v[34:35], off
	global_load_dword v232, v[36:37], off
	v_lshl_add_u64 v[36:37], s[0:1], 0, v[50:51]
	global_load_dword v233, v[36:37], off
	s_waitcnt vmcnt(0)
	v_cvt_pk_bf16_f32 v20, v202, v203
	v_cvt_pk_bf16_f32 v21, v204, v205
	v_cvt_pk_bf16_f32 v22, v206, v207
	v_cvt_pk_bf16_f32 v23, v208, v209
	v_cvt_pk_bf16_f32 v24, v210, v211
	v_cvt_pk_bf16_f32 v25, v212, v213
	v_cvt_pk_bf16_f32 v26, v214, v215
	v_cvt_pk_bf16_f32 v27, v216, v217
	v_cvt_pk_bf16_f32 v28, v218, v219
	v_cvt_pk_bf16_f32 v29, v220, v221
	v_cvt_pk_bf16_f32 v30, v222, v223
	v_cvt_pk_bf16_f32 v31, v224, v225
	v_cvt_pk_bf16_f32 v32, v227, v226
	v_cvt_pk_bf16_f32 v33, v228, v229
	v_cvt_pk_bf16_f32 v34, v230, v231
	v_cvt_pk_bf16_f32 v35, v232, v233
	v_or_b32_e32 v1, 16, v0
	v_add_u32_e32 v36, v55, v1
	v_ashrrev_i32_e32 v37, 31, v36
	v_lshlrev_b64 v[40:41], 2, v[36:37]
	v_lshl_add_u64 v[36:37], s[38:39], 0, v[40:41]
	global_load_dword v202, v[36:37], off
	v_add_u32_e32 v36, v55, v54
	v_ashrrev_i32_e32 v37, 31, v36
	v_lshlrev_b64 v[42:43], 2, v[36:37]
	v_lshl_add_u64 v[36:37], s[38:39], 0, v[42:43]
	global_load_dword v203, v[36:37], off
	v_lshl_add_u64 v[40:41], s[0:1], 0, v[40:41]
	v_add_u32_e32 v38, v55, v64
	v_ashrrev_i32_e32 v39, 31, v38
	v_lshlrev_b64 v[46:47], 2, v[38:39]
	v_lshl_add_u64 v[38:39], s[38:39], 0, v[46:47]
	global_load_dword v204, v[38:39], off
	v_add_u32_e32 v38, v55, v65
	v_ashrrev_i32_e32 v39, 31, v38
	v_lshlrev_b64 v[50:51], 2, v[38:39]
	v_lshl_add_u64 v[38:39], s[38:39], 0, v[50:51]
	global_load_dword v205, v[38:39], off
	v_add_u32_e32 v38, v55, v66
	v_ashrrev_i32_e32 v39, 31, v38
	v_lshlrev_b64 v[52:53], 2, v[38:39]
	v_lshl_add_u64 v[38:39], s[38:39], 0, v[52:53]
	global_load_dword v206, v[38:39], off
	v_add_u32_e32 v38, v55, v67
	v_ashrrev_i32_e32 v39, 31, v38
	v_lshlrev_b64 v[56:57], 2, v[38:39]
	v_lshl_add_u64 v[38:39], s[38:39], 0, v[56:57]
	global_load_dword v207, v[38:39], off
	v_add_u32_e32 v58, v55, v72
	v_ashrrev_i32_e32 v59, 31, v58
	v_lshlrev_b64 v[58:59], 2, v[58:59]
	v_lshl_add_u64 v[60:61], s[38:39], 0, v[58:59]
	global_load_dword v208, v[60:61], off
	v_add_u32_e32 v60, v55, v73
	v_ashrrev_i32_e32 v61, 31, v60
	v_lshlrev_b64 v[60:61], 2, v[60:61]
	v_lshl_add_u64 v[62:63], s[38:39], 0, v[60:61]
	global_load_dword v209, v[62:63], off
	global_load_dword v210, v[40:41], off
	v_lshl_add_u64 v[40:41], s[0:1], 0, v[42:43]
	v_lshl_add_u64 v[42:43], s[0:1], 0, v[46:47]
	global_load_dword v211, v[40:41], off
	global_load_dword v212, v[42:43], off
	v_lshl_add_u64 v[42:43], s[0:1], 0, v[50:51]
	global_load_dword v213, v[42:43], off
	v_add_u32_e32 v62, v2, v72
	v_ashrrev_i32_e32 v63, 31, v62
	v_lshlrev_b64 v[62:63], 2, v[62:63]
	v_lshl_add_u64 v[42:43], s[0:1], 0, v[52:53]
	global_load_dword v214, v[42:43], off
	v_lshl_add_u64 v[42:43], s[0:1], 0, v[56:57]
	global_load_dword v215, v[42:43], off
	v_lshl_add_u64 v[46:47], s[0:1], 0, v[58:59]
	global_load_dword v216, v[46:47], off
	v_lshl_add_u64 v[46:47], s[0:1], 0, v[60:61]
	global_load_dword v217, v[46:47], off
	global_load_dword v218, v[44:45], off offset:64
	v_add_u32_e32 v44, v2, v54
	v_ashrrev_i32_e32 v45, 31, v44
	v_lshlrev_b64 v[50:51], 2, v[44:45]
	v_lshl_add_u64 v[44:45], s[38:39], 0, v[50:51]
	global_load_dword v219, v[44:45], off
	v_add_u32_e32 v46, v2, v64
	v_ashrrev_i32_e32 v47, 31, v46
	v_lshlrev_b64 v[52:53], 2, v[46:47]
	v_lshl_add_u64 v[46:47], s[38:39], 0, v[52:53]
	global_load_dword v220, v[46:47], off
	v_add_u32_e32 v46, v2, v65
	v_ashrrev_i32_e32 v47, 31, v46
	v_lshlrev_b64 v[56:57], 2, v[46:47]
	v_lshl_add_u64 v[46:47], s[38:39], 0, v[56:57]
	global_load_dword v221, v[46:47], off
	v_lshl_add_u64 v[64:65], s[38:39], 0, v[62:63]
	v_add_u32_e32 v46, v2, v66
	v_ashrrev_i32_e32 v47, 31, v46
	v_lshlrev_b64 v[58:59], 2, v[46:47]
	v_lshl_add_u64 v[46:47], s[38:39], 0, v[58:59]
	global_load_dword v222, v[46:47], off
	v_add_u32_e32 v46, v2, v67
	v_ashrrev_i32_e32 v47, 31, v46
	v_lshlrev_b64 v[60:61], 2, v[46:47]
	v_lshl_add_u64 v[46:47], s[38:39], 0, v[60:61]
	global_load_dword v223, v[46:47], off
	global_load_dword v224, v[64:65], off
	v_add_u32_e32 v64, v2, v73
	v_ashrrev_i32_e32 v65, 31, v64
	v_lshlrev_b64 v[64:65], 2, v[64:65]
	v_lshl_add_u64 v[66:67], s[38:39], 0, v[64:65]
	global_load_dword v225, v[66:67], off
	global_load_dword v226, v[48:49], off offset:64
	v_lshl_add_u64 v[48:49], s[0:1], 0, v[50:51]
	v_lshl_add_u64 v[50:51], s[0:1], 0, v[52:53]
	global_load_dword v227, v[48:49], off
	global_load_dword v228, v[50:51], off
	v_lshl_add_u64 v[50:51], s[0:1], 0, v[56:57]
	global_load_dword v229, v[50:51], off
	v_lshl_add_u64 v[50:51], s[0:1], 0, v[58:59]
	global_load_dword v230, v[50:51], off
	v_lshl_add_u64 v[50:51], s[0:1], 0, v[60:61]
	global_load_dword v231, v[50:51], off
	v_add_u32_e32 v60, v55, v81
	v_ashrrev_i32_e32 v61, 31, v60
	v_lshlrev_b64 v[60:61], 2, v[60:61]
	v_lshl_add_u64 v[52:53], s[0:1], 0, v[62:63]
	global_load_dword v232, v[52:53], off
	v_lshl_add_u64 v[52:53], s[0:1], 0, v[64:65]
	global_load_dword v233, v[52:53], off
	v_lshl_add_u64 v[62:63], s[38:39], 0, v[60:61]
	s_waitcnt vmcnt(0)
	v_cvt_pk_bf16_f32 v36, v202, v203
	v_cvt_pk_bf16_f32 v37, v204, v205
	v_cvt_pk_bf16_f32 v38, v206, v207
	v_cvt_pk_bf16_f32 v39, v208, v209
	v_cvt_pk_bf16_f32 v40, v210, v211
	v_cvt_pk_bf16_f32 v41, v212, v213
	v_cvt_pk_bf16_f32 v42, v214, v215
	v_cvt_pk_bf16_f32 v43, v216, v217
	v_cvt_pk_bf16_f32 v44, v218, v219
	v_cvt_pk_bf16_f32 v45, v220, v221
	v_cvt_pk_bf16_f32 v46, v222, v223
	v_cvt_pk_bf16_f32 v47, v224, v225
	v_cvt_pk_bf16_f32 v48, v226, v227
	v_cvt_pk_bf16_f32 v49, v228, v229
	v_cvt_pk_bf16_f32 v50, v230, v231
	v_cvt_pk_bf16_f32 v51, v232, v233
	v_add_u32_e32 v52, v55, v0
	v_ashrrev_i32_e32 v53, 31, v52
	v_lshlrev_b64 v[56:57], 2, v[52:53]
	v_lshl_add_u64 v[52:53], s[38:39], 0, v[56:57]
	global_load_dword v202, v[52:53], off
	v_add_u32_e32 v52, v55, v80
	v_ashrrev_i32_e32 v53, 31, v52
	v_lshlrev_b64 v[58:59], 2, v[52:53]
	v_lshl_add_u64 v[52:53], s[38:39], 0, v[58:59]
	global_load_dword v203, v[52:53], off
	v_lshl_add_u64 v[56:57], s[0:1], 0, v[56:57]
	global_load_dword v204, v[62:63], off
	v_add_u32_e32 v62, v55, v82
	v_ashrrev_i32_e32 v63, 31, v62
	v_lshlrev_b64 v[62:63], 2, v[62:63]
	v_lshl_add_u64 v[64:65], s[38:39], 0, v[62:63]
	global_load_dword v205, v[64:65], off
	v_add_u32_e32 v64, v55, v83
	v_ashrrev_i32_e32 v65, 31, v64
	v_lshlrev_b64 v[64:65], 2, v[64:65]
	v_lshl_add_u64 v[66:67], s[38:39], 0, v[64:65]
	global_load_dword v206, v[66:67], off
	v_add_u32_e32 v66, v55, v84
	v_ashrrev_i32_e32 v67, 31, v66
	v_lshlrev_b64 v[66:67], 2, v[66:67]
	v_lshl_add_u64 v[72:73], s[38:39], 0, v[66:67]
	global_load_dword v207, v[72:73], off
	v_add_u32_e32 v72, v55, v85
	v_ashrrev_i32_e32 v73, 31, v72
	v_lshlrev_b64 v[72:73], 2, v[72:73]
	v_lshl_add_u64 v[74:75], s[38:39], 0, v[72:73]
	global_load_dword v208, v[74:75], off
	v_add_u32_e32 v74, v55, v87
	v_ashrrev_i32_e32 v75, 31, v74
	v_lshlrev_b64 v[74:75], 2, v[74:75]
	v_lshl_add_u64 v[78:79], s[38:39], 0, v[74:75]
	global_load_dword v209, v[78:79], off
	global_load_dword v210, v[56:57], off
	v_lshl_add_u64 v[56:57], s[0:1], 0, v[58:59]
	v_lshl_add_u64 v[58:59], s[0:1], 0, v[60:61]
	global_load_dword v211, v[56:57], off
	global_load_dword v212, v[58:59], off
	v_lshl_add_u64 v[58:59], s[0:1], 0, v[62:63]
	global_load_dword v213, v[58:59], off
	v_lshl_add_u64 v[58:59], s[0:1], 0, v[64:65]
	global_load_dword v214, v[58:59], off
	v_lshl_add_u64 v[58:59], s[0:1], 0, v[66:67]
	global_load_dword v215, v[58:59], off
	v_lshl_add_u64 v[60:61], s[0:1], 0, v[72:73]
	global_load_dword v216, v[60:61], off
	v_lshl_add_u64 v[60:61], s[0:1], 0, v[74:75]
	global_load_dword v217, v[60:61], off
	v_add_u32_e32 v60, v2, v0
	v_ashrrev_i32_e32 v61, 31, v60
	v_lshlrev_b64 v[64:65], 2, v[60:61]
	v_lshl_add_u64 v[60:61], s[38:39], 0, v[64:65]
	global_load_dword v218, v[60:61], off
	v_add_u32_e32 v60, v2, v80
	v_ashrrev_i32_e32 v61, 31, v60
	v_lshlrev_b64 v[66:67], 2, v[60:61]
	v_lshl_add_u64 v[60:61], s[38:39], 0, v[66:67]
	global_load_dword v219, v[60:61], off
	v_lshl_add_u64 v[64:65], s[0:1], 0, v[64:65]
	v_add_u32_e32 v62, v2, v81
	v_ashrrev_i32_e32 v63, 31, v62
	v_lshlrev_b64 v[72:73], 2, v[62:63]
	v_lshl_add_u64 v[62:63], s[38:39], 0, v[72:73]
	global_load_dword v220, v[62:63], off
	v_add_u32_e32 v62, v2, v82
	v_ashrrev_i32_e32 v63, 31, v62
	v_lshlrev_b64 v[74:75], 2, v[62:63]
	v_lshl_add_u64 v[62:63], s[38:39], 0, v[74:75]
	global_load_dword v221, v[62:63], off
	v_add_u32_e32 v62, v2, v83
	v_ashrrev_i32_e32 v63, 31, v62
	v_lshlrev_b64 v[78:79], 2, v[62:63]
	v_lshl_add_u64 v[62:63], s[38:39], 0, v[78:79]
	global_load_dword v222, v[62:63], off
	v_add_u32_e32 v62, v2, v84
	v_ashrrev_i32_e32 v63, 31, v62
	v_lshlrev_b64 v[80:81], 2, v[62:63]
	v_lshl_add_u64 v[62:63], s[38:39], 0, v[80:81]
	global_load_dword v223, v[62:63], off
	v_add_u32_e32 v82, v2, v85
	v_ashrrev_i32_e32 v83, 31, v82
	v_lshlrev_b64 v[82:83], 2, v[82:83]
	v_lshl_add_u64 v[84:85], s[38:39], 0, v[82:83]
	global_load_dword v224, v[84:85], off
	v_add_u32_e32 v84, v2, v87
	v_ashrrev_i32_e32 v85, 31, v84
	v_lshlrev_b64 v[84:85], 2, v[84:85]
	v_lshl_add_u64 v[86:87], s[38:39], 0, v[84:85]
	global_load_dword v225, v[86:87], off
	v_mov_b32_e32 v87, v3
	v_cmp_gt_u32_e64 s[38:39], 64, v68
	global_load_dword v226, v[64:65], off
	v_lshl_add_u64 v[64:65], s[0:1], 0, v[66:67]
	global_load_dword v227, v[64:65], off
	v_lshl_add_u64 v[66:67], s[0:1], 0, v[72:73]
	v_lshl_add_u64 v[72:73], s[0:1], 0, v[82:83]
	global_load_dword v228, v[66:67], off
	v_lshl_add_u64 v[66:67], s[0:1], 0, v[74:75]
	global_load_dword v229, v[66:67], off
	v_lshl_add_u64 v[66:67], s[0:1], 0, v[78:79]
	v_ashrrev_i32_e32 v78, 7, v160
	v_lshlrev_b32_e32 v137, 3, v78
	v_lshlrev_b32_e32 v79, 4, v160
	v_and_b32_e32 v86, 0x1f0, v79
	v_lshlrev_b32_e32 v75, 8, v136
	v_lshl_or_b32 v145, v144, 9, v86
	v_add_u32_e32 v146, 16, v137
	v_lshl_add_u64 v[86:87], s[18:19], 0, v[86:87]
	global_load_dword v230, v[66:67], off
	v_lshl_add_u64 v[66:67], s[0:1], 0, v[80:81]
	global_load_dword v231, v[66:67], off
	v_add_u32_e32 v80, 0xffffff80, v160
	v_mov_b32_e32 v81, 0xea00
	v_lshl_add_u32 v143, v80, 5, v81
	global_load_dword v232, v[72:73], off
	v_lshl_add_u64 v[72:73], s[0:1], 0, v[84:85]
	global_load_dword v233, v[72:73], off
	s_movk_i32 s0, 0x80
	v_cmp_gt_u32_e32 vcc, s0, v160
	s_movk_i32 s0, 0x7f
	v_cmp_lt_i32_e64 s[42:43], s0, v160
	s_movk_i32 s0, 0x90
	v_cmp_gt_u32_e64 s[44:45], s0, v160
	v_readlane_b32 s0, v253, 39
	v_readlane_b32 s1, v253, 40
	s_load_dword s20, s[0:1], 0x0
	s_movk_i32 s0, 0x880
	v_mul_lo_u32 v97, v78, s0
	v_lshlrev_b32_e32 v73, 7, v139
	v_and_b32_e32 v84, 0xf0, v79
	v_mov_b32_e32 v85, v3
	v_lshl_add_u64 v[82:83], s[72:73], 0, v[84:85]
	s_waitcnt lgkmcnt(0)
	s_lshl_b32 s58, s20, 6
	v_add_u32_e32 v157, v94, v97
	s_waitcnt vmcnt(0)
	v_cvt_pk_bf16_f32 v52, v202, v203
	v_cvt_pk_bf16_f32 v53, v204, v205
	v_cvt_pk_bf16_f32 v54, v206, v207
	v_cvt_pk_bf16_f32 v55, v208, v209
	v_cvt_pk_bf16_f32 v56, v210, v211
	v_cvt_pk_bf16_f32 v57, v212, v213
	v_cvt_pk_bf16_f32 v58, v214, v215
	v_cvt_pk_bf16_f32 v59, v216, v217
	v_cvt_pk_bf16_f32 v60, v218, v219
	v_cvt_pk_bf16_f32 v61, v220, v221
	v_cvt_pk_bf16_f32 v62, v222, v223
	v_cvt_pk_bf16_f32 v63, v224, v225
	v_cvt_pk_bf16_f32 v64, v226, v227
	v_cvt_pk_bf16_f32 v65, v228, v229
	v_cvt_pk_bf16_f32 v66, v230, v231
	v_cvt_pk_bf16_f32 v67, v232, v233
	v_lshlrev_b32_e32 v2, 9, v70
	v_lshl_or_b32 v72, v78, 12, v2
	v_mul_u32_u24_e32 v78, 0x410, v136
	v_add_lshl_u32 v147, v78, v0, 2
	v_add_lshl_u32 v148, v78, v1, 2
	v_mov_b32_e32 v0, s69
	v_mov_b32_e32 v1, s65
	v_add_lshl_u32 v149, v78, v77, 2
	v_add_lshl_u32 v150, v78, v76, 2
	v_cndmask_b32_e32 v1, v0, v1, vcc
	v_mov_b32_e32 v0, s68
	v_mov_b32_e32 v78, s64
	v_and_b32_e32 v2, 0x70, v79
	v_cndmask_b32_e32 v0, v0, v78, vcc
	v_mov_b32_e32 v78, s71
	v_mov_b32_e32 v79, s67
	v_or3_b32 v140, v72, v73, v2
	v_ashrrev_i32_e32 v72, 6, v160
	v_cndmask_b32_e32 v93, v78, v79, vcc
	v_mov_b32_e32 v78, s70
	v_mov_b32_e32 v79, s66
	v_lshlrev_b32_e32 v74, 10, v72
	v_cndmask_b32_e32 v92, v78, v79, vcc
	v_or3_b32 v141, v74, v75, v84
	v_lshrrev_b32_e32 v74, 2, v80
	v_lshl_add_u64 v[78:79], v[0:1], 0, v[2:3]
	v_lshl_add_u64 v[80:81], v[92:93], 0, v[2:3]
	v_mov_b32_e32 v2, 0x2000
	v_lshl_add_u32 v153, v160, 2, v2
	v_and_b32_e32 v2, 7, v160
	v_lshlrev_b32_e32 v2, 4, v2
	v_ashrrev_i32_e32 v73, 31, v72
	v_mov_b32_e32 v75, v3
	v_lshl_add_u64 v[76:77], v[160:161], 1, s[18:19]
	v_lshl_add_u64 v[84:85], s[74:75], 0, v[84:85]
	v_lshl_add_u64 v[90:91], v[0:1], 0, v[2:3]
	v_lshl_add_u64 v[92:93], v[92:93], 0, v[2:3]
	s_branch .LBB0_174
